# fused-norm epilogues: acquire fence after the row-statistics poll removed (statistics are stored and loaded write-through sc1 on both sides)
# speedup vs baseline: 1.0211x; 1.0026x over previous
.LBB0_371:
	s_nop 0
